# phase0 silu(c) modulation loop: all 36 loads issued up front, straight-line silu
# baseline (speedup 1.0000x reference)
.LBB0_6:
	v_lshlrev_b32_e32 v13, 2, v50
	global_load_dword v110, v13, s[2:3]
	v_add_u32_e32 v13, 0x400, v13
	global_load_dword v111, v13, s[2:3]
	v_add_u32_e32 v13, 0x400, v13
	global_load_dword v112, v13, s[2:3]
	v_add_u32_e32 v13, 0x400, v13
	global_load_dword v113, v13, s[2:3]
	v_add_u32_e32 v13, 0x400, v13
	global_load_dword v114, v13, s[2:3]
	v_add_u32_e32 v13, 0x400, v13
	global_load_dword v115, v13, s[2:3]
	v_add_u32_e32 v13, 0x400, v13
	global_load_dword v116, v13, s[2:3]
	v_add_u32_e32 v13, 0x400, v13
	global_load_dword v117, v13, s[2:3]
	v_add_u32_e32 v13, 0x400, v13
	global_load_dword v118, v13, s[2:3]
	v_add_u32_e32 v13, 0x400, v13
	global_load_dword v119, v13, s[2:3]
	v_add_u32_e32 v13, 0x400, v13
	global_load_dword v120, v13, s[2:3]
	v_add_u32_e32 v13, 0x400, v13
	global_load_dword v121, v13, s[2:3]
	v_add_u32_e32 v13, 0x400, v13
	global_load_dword v122, v13, s[2:3]
	v_add_u32_e32 v13, 0x400, v13
	global_load_dword v123, v13, s[2:3]
	v_add_u32_e32 v13, 0x400, v13
	global_load_dword v124, v13, s[2:3]
	v_add_u32_e32 v13, 0x400, v13
	global_load_dword v125, v13, s[2:3]
	v_add_u32_e32 v13, 0x400, v13
	global_load_dword v126, v13, s[2:3]
	v_add_u32_e32 v13, 0x400, v13
	global_load_dword v127, v13, s[2:3]
	v_add_u32_e32 v13, 0x400, v13
	global_load_dword v128, v13, s[2:3]
	v_add_u32_e32 v13, 0x400, v13
	global_load_dword v129, v13, s[2:3]
	v_add_u32_e32 v13, 0x400, v13
	global_load_dword v130, v13, s[2:3]
	v_add_u32_e32 v13, 0x400, v13
	global_load_dword v131, v13, s[2:3]
	v_add_u32_e32 v13, 0x400, v13
	global_load_dword v132, v13, s[2:3]
	v_add_u32_e32 v13, 0x400, v13
	global_load_dword v133, v13, s[2:3]
	v_add_u32_e32 v13, 0x400, v13
	global_load_dword v134, v13, s[2:3]
	v_add_u32_e32 v13, 0x400, v13
	global_load_dword v135, v13, s[2:3]
	v_add_u32_e32 v13, 0x400, v13
	global_load_dword v136, v13, s[2:3]
	v_add_u32_e32 v13, 0x400, v13
	global_load_dword v137, v13, s[2:3]
	v_add_u32_e32 v13, 0x400, v13
	global_load_dword v138, v13, s[2:3]
	v_add_u32_e32 v13, 0x400, v13
	global_load_dword v139, v13, s[2:3]
	v_add_u32_e32 v13, 0x400, v13
	global_load_dword v140, v13, s[2:3]
	v_add_u32_e32 v13, 0x400, v13
	global_load_dword v141, v13, s[2:3]
	v_lshlrev_b32_e32 v13, 2, v50
	global_load_dword v142, v13, s[4:5]
	global_load_dword v143, v13, s[4:5] offset:1024
	global_load_dword v144, v13, s[4:5] offset:2048
	global_load_dword v145, v13, s[4:5] offset:3072
	s_waitcnt vmcnt(35)
	v_mul_f32_e32 v7, 0xbfb8aa3b, v110
	v_exp_f32_e32 v7, v7
	s_nop 0
	v_add_f32_e32 v7, 1.0, v7
	v_div_scale_f32 v8, s[28:29], v7, v7, v110
	v_rcp_f32_e32 v9, v8
	v_div_scale_f32 v10, vcc, v110, v7, v110
	v_fma_f32 v11, -v8, v9, 1.0
	v_fmac_f32_e32 v9, v11, v9
	v_mul_f32_e32 v11, v10, v9
	v_fma_f32 v12, -v8, v11, v10
	v_fmac_f32_e32 v11, v12, v9
	v_fma_f32 v8, -v8, v11, v10
	v_div_fmas_f32 v8, v8, v9, v11
	v_div_fixup_f32 v4, v8, v7, v110
	ds_write_b32 v1, v4
	v_add_u32_e32 v1, 0x400, v1
	s_waitcnt vmcnt(34)
	v_mul_f32_e32 v7, 0xbfb8aa3b, v111
	v_exp_f32_e32 v7, v7
	s_nop 0
	v_add_f32_e32 v7, 1.0, v7
	v_div_scale_f32 v8, s[28:29], v7, v7, v111
	v_rcp_f32_e32 v9, v8
	v_div_scale_f32 v10, vcc, v111, v7, v111
	v_fma_f32 v11, -v8, v9, 1.0
	v_fmac_f32_e32 v9, v11, v9
	v_mul_f32_e32 v11, v10, v9
	v_fma_f32 v12, -v8, v11, v10
	v_fmac_f32_e32 v11, v12, v9
	v_fma_f32 v8, -v8, v11, v10
	v_div_fmas_f32 v8, v8, v9, v11
	v_div_fixup_f32 v4, v8, v7, v111
	ds_write_b32 v1, v4
	v_add_u32_e32 v1, 0x400, v1
	s_waitcnt vmcnt(33)
	v_mul_f32_e32 v7, 0xbfb8aa3b, v112
	v_exp_f32_e32 v7, v7
	s_nop 0
	v_add_f32_e32 v7, 1.0, v7
	v_div_scale_f32 v8, s[28:29], v7, v7, v112
	v_rcp_f32_e32 v9, v8
	v_div_scale_f32 v10, vcc, v112, v7, v112
	v_fma_f32 v11, -v8, v9, 1.0
	v_fmac_f32_e32 v9, v11, v9
	v_mul_f32_e32 v11, v10, v9
	v_fma_f32 v12, -v8, v11, v10
	v_fmac_f32_e32 v11, v12, v9
	v_fma_f32 v8, -v8, v11, v10
	v_div_fmas_f32 v8, v8, v9, v11
	v_div_fixup_f32 v4, v8, v7, v112
	ds_write_b32 v1, v4
	v_add_u32_e32 v1, 0x400, v1
	s_waitcnt vmcnt(32)
	v_mul_f32_e32 v7, 0xbfb8aa3b, v113
	v_exp_f32_e32 v7, v7
	s_nop 0
	v_add_f32_e32 v7, 1.0, v7
	v_div_scale_f32 v8, s[28:29], v7, v7, v113
	v_rcp_f32_e32 v9, v8
	v_div_scale_f32 v10, vcc, v113, v7, v113
	v_fma_f32 v11, -v8, v9, 1.0
	v_fmac_f32_e32 v9, v11, v9
	v_mul_f32_e32 v11, v10, v9
	v_fma_f32 v12, -v8, v11, v10
	v_fmac_f32_e32 v11, v12, v9
	v_fma_f32 v8, -v8, v11, v10
	v_div_fmas_f32 v8, v8, v9, v11
	v_div_fixup_f32 v4, v8, v7, v113
	ds_write_b32 v1, v4
	v_add_u32_e32 v1, 0x400, v1
	s_waitcnt vmcnt(31)
	v_mul_f32_e32 v7, 0xbfb8aa3b, v114
	v_exp_f32_e32 v7, v7
	s_nop 0
	v_add_f32_e32 v7, 1.0, v7
	v_div_scale_f32 v8, s[28:29], v7, v7, v114
	v_rcp_f32_e32 v9, v8
	v_div_scale_f32 v10, vcc, v114, v7, v114
	v_fma_f32 v11, -v8, v9, 1.0
	v_fmac_f32_e32 v9, v11, v9
	v_mul_f32_e32 v11, v10, v9
	v_fma_f32 v12, -v8, v11, v10
	v_fmac_f32_e32 v11, v12, v9
	v_fma_f32 v8, -v8, v11, v10
	v_div_fmas_f32 v8, v8, v9, v11
	v_div_fixup_f32 v4, v8, v7, v114
	ds_write_b32 v1, v4
	v_add_u32_e32 v1, 0x400, v1
	s_waitcnt vmcnt(30)
	v_mul_f32_e32 v7, 0xbfb8aa3b, v115
	v_exp_f32_e32 v7, v7
	s_nop 0
	v_add_f32_e32 v7, 1.0, v7
	v_div_scale_f32 v8, s[28:29], v7, v7, v115
	v_rcp_f32_e32 v9, v8
	v_div_scale_f32 v10, vcc, v115, v7, v115
	v_fma_f32 v11, -v8, v9, 1.0
	v_fmac_f32_e32 v9, v11, v9
	v_mul_f32_e32 v11, v10, v9
	v_fma_f32 v12, -v8, v11, v10
	v_fmac_f32_e32 v11, v12, v9
	v_fma_f32 v8, -v8, v11, v10
	v_div_fmas_f32 v8, v8, v9, v11
	v_div_fixup_f32 v4, v8, v7, v115
	ds_write_b32 v1, v4
	v_add_u32_e32 v1, 0x400, v1
	s_waitcnt vmcnt(29)
	v_mul_f32_e32 v7, 0xbfb8aa3b, v116
	v_exp_f32_e32 v7, v7
	s_nop 0
	v_add_f32_e32 v7, 1.0, v7
	v_div_scale_f32 v8, s[28:29], v7, v7, v116
	v_rcp_f32_e32 v9, v8
	v_div_scale_f32 v10, vcc, v116, v7, v116
	v_fma_f32 v11, -v8, v9, 1.0
	v_fmac_f32_e32 v9, v11, v9
	v_mul_f32_e32 v11, v10, v9
	v_fma_f32 v12, -v8, v11, v10
	v_fmac_f32_e32 v11, v12, v9
	v_fma_f32 v8, -v8, v11, v10
	v_div_fmas_f32 v8, v8, v9, v11
	v_div_fixup_f32 v4, v8, v7, v116
	ds_write_b32 v1, v4
	v_add_u32_e32 v1, 0x400, v1
	s_waitcnt vmcnt(28)
	v_mul_f32_e32 v7, 0xbfb8aa3b, v117
	v_exp_f32_e32 v7, v7
	s_nop 0
	v_add_f32_e32 v7, 1.0, v7
	v_div_scale_f32 v8, s[28:29], v7, v7, v117
	v_rcp_f32_e32 v9, v8
	v_div_scale_f32 v10, vcc, v117, v7, v117
	v_fma_f32 v11, -v8, v9, 1.0
	v_fmac_f32_e32 v9, v11, v9
	v_mul_f32_e32 v11, v10, v9
	v_fma_f32 v12, -v8, v11, v10
	v_fmac_f32_e32 v11, v12, v9
	v_fma_f32 v8, -v8, v11, v10
	v_div_fmas_f32 v8, v8, v9, v11
	v_div_fixup_f32 v4, v8, v7, v117
	ds_write_b32 v1, v4
	v_add_u32_e32 v1, 0x400, v1
	s_waitcnt vmcnt(27)
	v_mul_f32_e32 v7, 0xbfb8aa3b, v118
	v_exp_f32_e32 v7, v7
	s_nop 0
	v_add_f32_e32 v7, 1.0, v7
	v_div_scale_f32 v8, s[28:29], v7, v7, v118
	v_rcp_f32_e32 v9, v8
	v_div_scale_f32 v10, vcc, v118, v7, v118
	v_fma_f32 v11, -v8, v9, 1.0
	v_fmac_f32_e32 v9, v11, v9
	v_mul_f32_e32 v11, v10, v9
	v_fma_f32 v12, -v8, v11, v10
	v_fmac_f32_e32 v11, v12, v9
	v_fma_f32 v8, -v8, v11, v10
	v_div_fmas_f32 v8, v8, v9, v11
	v_div_fixup_f32 v4, v8, v7, v118
	ds_write_b32 v1, v4
	v_add_u32_e32 v1, 0x400, v1
	s_waitcnt vmcnt(26)
	v_mul_f32_e32 v7, 0xbfb8aa3b, v119
	v_exp_f32_e32 v7, v7
	s_nop 0
	v_add_f32_e32 v7, 1.0, v7
	v_div_scale_f32 v8, s[28:29], v7, v7, v119
	v_rcp_f32_e32 v9, v8
	v_div_scale_f32 v10, vcc, v119, v7, v119
	v_fma_f32 v11, -v8, v9, 1.0
	v_fmac_f32_e32 v9, v11, v9
	v_mul_f32_e32 v11, v10, v9
	v_fma_f32 v12, -v8, v11, v10
	v_fmac_f32_e32 v11, v12, v9
	v_fma_f32 v8, -v8, v11, v10
	v_div_fmas_f32 v8, v8, v9, v11
	v_div_fixup_f32 v4, v8, v7, v119
	ds_write_b32 v1, v4
	v_add_u32_e32 v1, 0x400, v1
	s_waitcnt vmcnt(25)
	v_mul_f32_e32 v7, 0xbfb8aa3b, v120
	v_exp_f32_e32 v7, v7
	s_nop 0
	v_add_f32_e32 v7, 1.0, v7
	v_div_scale_f32 v8, s[28:29], v7, v7, v120
	v_rcp_f32_e32 v9, v8
	v_div_scale_f32 v10, vcc, v120, v7, v120
	v_fma_f32 v11, -v8, v9, 1.0
	v_fmac_f32_e32 v9, v11, v9
	v_mul_f32_e32 v11, v10, v9
	v_fma_f32 v12, -v8, v11, v10
	v_fmac_f32_e32 v11, v12, v9
	v_fma_f32 v8, -v8, v11, v10
	v_div_fmas_f32 v8, v8, v9, v11
	v_div_fixup_f32 v4, v8, v7, v120
	ds_write_b32 v1, v4
	v_add_u32_e32 v1, 0x400, v1
	s_waitcnt vmcnt(24)
	v_mul_f32_e32 v7, 0xbfb8aa3b, v121
	v_exp_f32_e32 v7, v7
	s_nop 0
	v_add_f32_e32 v7, 1.0, v7
	v_div_scale_f32 v8, s[28:29], v7, v7, v121
	v_rcp_f32_e32 v9, v8
	v_div_scale_f32 v10, vcc, v121, v7, v121
	v_fma_f32 v11, -v8, v9, 1.0
	v_fmac_f32_e32 v9, v11, v9
	v_mul_f32_e32 v11, v10, v9
	v_fma_f32 v12, -v8, v11, v10
	v_fmac_f32_e32 v11, v12, v9
	v_fma_f32 v8, -v8, v11, v10
	v_div_fmas_f32 v8, v8, v9, v11
	v_div_fixup_f32 v4, v8, v7, v121
	ds_write_b32 v1, v4
	v_add_u32_e32 v1, 0x400, v1
	s_waitcnt vmcnt(23)
	v_mul_f32_e32 v7, 0xbfb8aa3b, v122
	v_exp_f32_e32 v7, v7
	s_nop 0
	v_add_f32_e32 v7, 1.0, v7
	v_div_scale_f32 v8, s[28:29], v7, v7, v122
	v_rcp_f32_e32 v9, v8
	v_div_scale_f32 v10, vcc, v122, v7, v122
	v_fma_f32 v11, -v8, v9, 1.0
	v_fmac_f32_e32 v9, v11, v9
	v_mul_f32_e32 v11, v10, v9
	v_fma_f32 v12, -v8, v11, v10
	v_fmac_f32_e32 v11, v12, v9
	v_fma_f32 v8, -v8, v11, v10
	v_div_fmas_f32 v8, v8, v9, v11
	v_div_fixup_f32 v4, v8, v7, v122
	ds_write_b32 v1, v4
	v_add_u32_e32 v1, 0x400, v1
	s_waitcnt vmcnt(22)
	v_mul_f32_e32 v7, 0xbfb8aa3b, v123
	v_exp_f32_e32 v7, v7
	s_nop 0
	v_add_f32_e32 v7, 1.0, v7
	v_div_scale_f32 v8, s[28:29], v7, v7, v123
	v_rcp_f32_e32 v9, v8
	v_div_scale_f32 v10, vcc, v123, v7, v123
	v_fma_f32 v11, -v8, v9, 1.0
	v_fmac_f32_e32 v9, v11, v9
	v_mul_f32_e32 v11, v10, v9
	v_fma_f32 v12, -v8, v11, v10
	v_fmac_f32_e32 v11, v12, v9
	v_fma_f32 v8, -v8, v11, v10
	v_div_fmas_f32 v8, v8, v9, v11
	v_div_fixup_f32 v4, v8, v7, v123
	ds_write_b32 v1, v4
	v_add_u32_e32 v1, 0x400, v1
	s_waitcnt vmcnt(21)
	v_mul_f32_e32 v7, 0xbfb8aa3b, v124
	v_exp_f32_e32 v7, v7
	s_nop 0
	v_add_f32_e32 v7, 1.0, v7
	v_div_scale_f32 v8, s[28:29], v7, v7, v124
	v_rcp_f32_e32 v9, v8
	v_div_scale_f32 v10, vcc, v124, v7, v124
	v_fma_f32 v11, -v8, v9, 1.0
	v_fmac_f32_e32 v9, v11, v9
	v_mul_f32_e32 v11, v10, v9
	v_fma_f32 v12, -v8, v11, v10
	v_fmac_f32_e32 v11, v12, v9
	v_fma_f32 v8, -v8, v11, v10
	v_div_fmas_f32 v8, v8, v9, v11
	v_div_fixup_f32 v4, v8, v7, v124
	ds_write_b32 v1, v4
	v_add_u32_e32 v1, 0x400, v1
	s_waitcnt vmcnt(20)
	v_mul_f32_e32 v7, 0xbfb8aa3b, v125
	v_exp_f32_e32 v7, v7
	s_nop 0
	v_add_f32_e32 v7, 1.0, v7
	v_div_scale_f32 v8, s[28:29], v7, v7, v125
	v_rcp_f32_e32 v9, v8
	v_div_scale_f32 v10, vcc, v125, v7, v125
	v_fma_f32 v11, -v8, v9, 1.0
	v_fmac_f32_e32 v9, v11, v9
	v_mul_f32_e32 v11, v10, v9
	v_fma_f32 v12, -v8, v11, v10
	v_fmac_f32_e32 v11, v12, v9
	v_fma_f32 v8, -v8, v11, v10
	v_div_fmas_f32 v8, v8, v9, v11
	v_div_fixup_f32 v4, v8, v7, v125
	ds_write_b32 v1, v4
	v_add_u32_e32 v1, 0x400, v1
	s_waitcnt vmcnt(19)
	v_mul_f32_e32 v7, 0xbfb8aa3b, v126
	v_exp_f32_e32 v7, v7
	s_nop 0
	v_add_f32_e32 v7, 1.0, v7
	v_div_scale_f32 v8, s[28:29], v7, v7, v126
	v_rcp_f32_e32 v9, v8
	v_div_scale_f32 v10, vcc, v126, v7, v126
	v_fma_f32 v11, -v8, v9, 1.0
	v_fmac_f32_e32 v9, v11, v9
	v_mul_f32_e32 v11, v10, v9
	v_fma_f32 v12, -v8, v11, v10
	v_fmac_f32_e32 v11, v12, v9
	v_fma_f32 v8, -v8, v11, v10
	v_div_fmas_f32 v8, v8, v9, v11
	v_div_fixup_f32 v4, v8, v7, v126
	ds_write_b32 v1, v4
	v_add_u32_e32 v1, 0x400, v1
	s_waitcnt vmcnt(18)
	v_mul_f32_e32 v7, 0xbfb8aa3b, v127
	v_exp_f32_e32 v7, v7
	s_nop 0
	v_add_f32_e32 v7, 1.0, v7
	v_div_scale_f32 v8, s[28:29], v7, v7, v127
	v_rcp_f32_e32 v9, v8
	v_div_scale_f32 v10, vcc, v127, v7, v127
	v_fma_f32 v11, -v8, v9, 1.0
	v_fmac_f32_e32 v9, v11, v9
	v_mul_f32_e32 v11, v10, v9
	v_fma_f32 v12, -v8, v11, v10
	v_fmac_f32_e32 v11, v12, v9
	v_fma_f32 v8, -v8, v11, v10
	v_div_fmas_f32 v8, v8, v9, v11
	v_div_fixup_f32 v4, v8, v7, v127
	ds_write_b32 v1, v4
	v_add_u32_e32 v1, 0x400, v1
	s_waitcnt vmcnt(17)
	v_mul_f32_e32 v7, 0xbfb8aa3b, v128
	v_exp_f32_e32 v7, v7
	s_nop 0
	v_add_f32_e32 v7, 1.0, v7
	v_div_scale_f32 v8, s[28:29], v7, v7, v128
	v_rcp_f32_e32 v9, v8
	v_div_scale_f32 v10, vcc, v128, v7, v128
	v_fma_f32 v11, -v8, v9, 1.0
	v_fmac_f32_e32 v9, v11, v9
	v_mul_f32_e32 v11, v10, v9
	v_fma_f32 v12, -v8, v11, v10
	v_fmac_f32_e32 v11, v12, v9
	v_fma_f32 v8, -v8, v11, v10
	v_div_fmas_f32 v8, v8, v9, v11
	v_div_fixup_f32 v4, v8, v7, v128
	ds_write_b32 v1, v4
	v_add_u32_e32 v1, 0x400, v1
	s_waitcnt vmcnt(16)
	v_mul_f32_e32 v7, 0xbfb8aa3b, v129
	v_exp_f32_e32 v7, v7
	s_nop 0
	v_add_f32_e32 v7, 1.0, v7
	v_div_scale_f32 v8, s[28:29], v7, v7, v129
	v_rcp_f32_e32 v9, v8
	v_div_scale_f32 v10, vcc, v129, v7, v129
	v_fma_f32 v11, -v8, v9, 1.0
	v_fmac_f32_e32 v9, v11, v9
	v_mul_f32_e32 v11, v10, v9
	v_fma_f32 v12, -v8, v11, v10
	v_fmac_f32_e32 v11, v12, v9
	v_fma_f32 v8, -v8, v11, v10
	v_div_fmas_f32 v8, v8, v9, v11
	v_div_fixup_f32 v4, v8, v7, v129
	ds_write_b32 v1, v4
	v_add_u32_e32 v1, 0x400, v1
	s_waitcnt vmcnt(15)
	v_mul_f32_e32 v7, 0xbfb8aa3b, v130
	v_exp_f32_e32 v7, v7
	s_nop 0
	v_add_f32_e32 v7, 1.0, v7
	v_div_scale_f32 v8, s[28:29], v7, v7, v130
	v_rcp_f32_e32 v9, v8
	v_div_scale_f32 v10, vcc, v130, v7, v130
	v_fma_f32 v11, -v8, v9, 1.0
	v_fmac_f32_e32 v9, v11, v9
	v_mul_f32_e32 v11, v10, v9
	v_fma_f32 v12, -v8, v11, v10
	v_fmac_f32_e32 v11, v12, v9
	v_fma_f32 v8, -v8, v11, v10
	v_div_fmas_f32 v8, v8, v9, v11
	v_div_fixup_f32 v4, v8, v7, v130
	ds_write_b32 v1, v4
	v_add_u32_e32 v1, 0x400, v1
	s_waitcnt vmcnt(14)
	v_mul_f32_e32 v7, 0xbfb8aa3b, v131
	v_exp_f32_e32 v7, v7
	s_nop 0
	v_add_f32_e32 v7, 1.0, v7
	v_div_scale_f32 v8, s[28:29], v7, v7, v131
	v_rcp_f32_e32 v9, v8
	v_div_scale_f32 v10, vcc, v131, v7, v131
	v_fma_f32 v11, -v8, v9, 1.0
	v_fmac_f32_e32 v9, v11, v9
	v_mul_f32_e32 v11, v10, v9
	v_fma_f32 v12, -v8, v11, v10
	v_fmac_f32_e32 v11, v12, v9
	v_fma_f32 v8, -v8, v11, v10
	v_div_fmas_f32 v8, v8, v9, v11
	v_div_fixup_f32 v4, v8, v7, v131
	ds_write_b32 v1, v4
	v_add_u32_e32 v1, 0x400, v1
	s_waitcnt vmcnt(13)
	v_mul_f32_e32 v7, 0xbfb8aa3b, v132
	v_exp_f32_e32 v7, v7
	s_nop 0
	v_add_f32_e32 v7, 1.0, v7
	v_div_scale_f32 v8, s[28:29], v7, v7, v132
	v_rcp_f32_e32 v9, v8
	v_div_scale_f32 v10, vcc, v132, v7, v132
	v_fma_f32 v11, -v8, v9, 1.0
	v_fmac_f32_e32 v9, v11, v9
	v_mul_f32_e32 v11, v10, v9
	v_fma_f32 v12, -v8, v11, v10
	v_fmac_f32_e32 v11, v12, v9
	v_fma_f32 v8, -v8, v11, v10
	v_div_fmas_f32 v8, v8, v9, v11
	v_div_fixup_f32 v4, v8, v7, v132
	ds_write_b32 v1, v4
	v_add_u32_e32 v1, 0x400, v1
	s_waitcnt vmcnt(12)
	v_mul_f32_e32 v7, 0xbfb8aa3b, v133
	v_exp_f32_e32 v7, v7
	s_nop 0
	v_add_f32_e32 v7, 1.0, v7
	v_div_scale_f32 v8, s[28:29], v7, v7, v133
	v_rcp_f32_e32 v9, v8
	v_div_scale_f32 v10, vcc, v133, v7, v133
	v_fma_f32 v11, -v8, v9, 1.0
	v_fmac_f32_e32 v9, v11, v9
	v_mul_f32_e32 v11, v10, v9
	v_fma_f32 v12, -v8, v11, v10
	v_fmac_f32_e32 v11, v12, v9
	v_fma_f32 v8, -v8, v11, v10
	v_div_fmas_f32 v8, v8, v9, v11
	v_div_fixup_f32 v4, v8, v7, v133
	ds_write_b32 v1, v4
	v_add_u32_e32 v1, 0x400, v1
	s_waitcnt vmcnt(11)
	v_mul_f32_e32 v7, 0xbfb8aa3b, v134
	v_exp_f32_e32 v7, v7
	s_nop 0
	v_add_f32_e32 v7, 1.0, v7
	v_div_scale_f32 v8, s[28:29], v7, v7, v134
	v_rcp_f32_e32 v9, v8
	v_div_scale_f32 v10, vcc, v134, v7, v134
	v_fma_f32 v11, -v8, v9, 1.0
	v_fmac_f32_e32 v9, v11, v9
	v_mul_f32_e32 v11, v10, v9
	v_fma_f32 v12, -v8, v11, v10
	v_fmac_f32_e32 v11, v12, v9
	v_fma_f32 v8, -v8, v11, v10
	v_div_fmas_f32 v8, v8, v9, v11
	v_div_fixup_f32 v4, v8, v7, v134
	ds_write_b32 v1, v4
	v_add_u32_e32 v1, 0x400, v1
	s_waitcnt vmcnt(10)
	v_mul_f32_e32 v7, 0xbfb8aa3b, v135
	v_exp_f32_e32 v7, v7
	s_nop 0
	v_add_f32_e32 v7, 1.0, v7
	v_div_scale_f32 v8, s[28:29], v7, v7, v135
	v_rcp_f32_e32 v9, v8
	v_div_scale_f32 v10, vcc, v135, v7, v135
	v_fma_f32 v11, -v8, v9, 1.0
	v_fmac_f32_e32 v9, v11, v9
	v_mul_f32_e32 v11, v10, v9
	v_fma_f32 v12, -v8, v11, v10
	v_fmac_f32_e32 v11, v12, v9
	v_fma_f32 v8, -v8, v11, v10
	v_div_fmas_f32 v8, v8, v9, v11
	v_div_fixup_f32 v4, v8, v7, v135
	ds_write_b32 v1, v4
	v_add_u32_e32 v1, 0x400, v1
	s_waitcnt vmcnt(9)
	v_mul_f32_e32 v7, 0xbfb8aa3b, v136
	v_exp_f32_e32 v7, v7
	s_nop 0
	v_add_f32_e32 v7, 1.0, v7
	v_div_scale_f32 v8, s[28:29], v7, v7, v136
	v_rcp_f32_e32 v9, v8
	v_div_scale_f32 v10, vcc, v136, v7, v136
	v_fma_f32 v11, -v8, v9, 1.0
	v_fmac_f32_e32 v9, v11, v9
	v_mul_f32_e32 v11, v10, v9
	v_fma_f32 v12, -v8, v11, v10
	v_fmac_f32_e32 v11, v12, v9
	v_fma_f32 v8, -v8, v11, v10
	v_div_fmas_f32 v8, v8, v9, v11
	v_div_fixup_f32 v4, v8, v7, v136
	ds_write_b32 v1, v4
	v_add_u32_e32 v1, 0x400, v1
	s_waitcnt vmcnt(8)
	v_mul_f32_e32 v7, 0xbfb8aa3b, v137
	v_exp_f32_e32 v7, v7
	s_nop 0
	v_add_f32_e32 v7, 1.0, v7
	v_div_scale_f32 v8, s[28:29], v7, v7, v137
	v_rcp_f32_e32 v9, v8
	v_div_scale_f32 v10, vcc, v137, v7, v137
	v_fma_f32 v11, -v8, v9, 1.0
	v_fmac_f32_e32 v9, v11, v9
	v_mul_f32_e32 v11, v10, v9
	v_fma_f32 v12, -v8, v11, v10
	v_fmac_f32_e32 v11, v12, v9
	v_fma_f32 v8, -v8, v11, v10
	v_div_fmas_f32 v8, v8, v9, v11
	v_div_fixup_f32 v4, v8, v7, v137
	ds_write_b32 v1, v4
	v_add_u32_e32 v1, 0x400, v1
	s_waitcnt vmcnt(7)
	v_mul_f32_e32 v7, 0xbfb8aa3b, v138
	v_exp_f32_e32 v7, v7
	s_nop 0
	v_add_f32_e32 v7, 1.0, v7
	v_div_scale_f32 v8, s[28:29], v7, v7, v138
	v_rcp_f32_e32 v9, v8
	v_div_scale_f32 v10, vcc, v138, v7, v138
	v_fma_f32 v11, -v8, v9, 1.0
	v_fmac_f32_e32 v9, v11, v9
	v_mul_f32_e32 v11, v10, v9
	v_fma_f32 v12, -v8, v11, v10
	v_fmac_f32_e32 v11, v12, v9
	v_fma_f32 v8, -v8, v11, v10
	v_div_fmas_f32 v8, v8, v9, v11
	v_div_fixup_f32 v4, v8, v7, v138
	ds_write_b32 v1, v4
	v_add_u32_e32 v1, 0x400, v1
	s_waitcnt vmcnt(6)
	v_mul_f32_e32 v7, 0xbfb8aa3b, v139
	v_exp_f32_e32 v7, v7
	s_nop 0
	v_add_f32_e32 v7, 1.0, v7
	v_div_scale_f32 v8, s[28:29], v7, v7, v139
	v_rcp_f32_e32 v9, v8
	v_div_scale_f32 v10, vcc, v139, v7, v139
	v_fma_f32 v11, -v8, v9, 1.0
	v_fmac_f32_e32 v9, v11, v9
	v_mul_f32_e32 v11, v10, v9
	v_fma_f32 v12, -v8, v11, v10
	v_fmac_f32_e32 v11, v12, v9
	v_fma_f32 v8, -v8, v11, v10
	v_div_fmas_f32 v8, v8, v9, v11
	v_div_fixup_f32 v4, v8, v7, v139
	ds_write_b32 v1, v4
	v_add_u32_e32 v1, 0x400, v1
	s_waitcnt vmcnt(5)
	v_mul_f32_e32 v7, 0xbfb8aa3b, v140
	v_exp_f32_e32 v7, v7
	s_nop 0
	v_add_f32_e32 v7, 1.0, v7
	v_div_scale_f32 v8, s[28:29], v7, v7, v140
	v_rcp_f32_e32 v9, v8
	v_div_scale_f32 v10, vcc, v140, v7, v140
	v_fma_f32 v11, -v8, v9, 1.0
	v_fmac_f32_e32 v9, v11, v9
	v_mul_f32_e32 v11, v10, v9
	v_fma_f32 v12, -v8, v11, v10
	v_fmac_f32_e32 v11, v12, v9
	v_fma_f32 v8, -v8, v11, v10
	v_div_fmas_f32 v8, v8, v9, v11
	v_div_fixup_f32 v4, v8, v7, v140
	ds_write_b32 v1, v4
	v_add_u32_e32 v1, 0x400, v1
	s_waitcnt vmcnt(4)
	v_mul_f32_e32 v7, 0xbfb8aa3b, v141
	v_exp_f32_e32 v7, v7
	s_nop 0
	v_add_f32_e32 v7, 1.0, v7
	v_div_scale_f32 v8, s[28:29], v7, v7, v141
	v_rcp_f32_e32 v9, v8
	v_div_scale_f32 v10, vcc, v141, v7, v141
	v_fma_f32 v11, -v8, v9, 1.0
	v_fmac_f32_e32 v9, v11, v9
	v_mul_f32_e32 v11, v10, v9
	v_fma_f32 v12, -v8, v11, v10
	v_fmac_f32_e32 v11, v12, v9
	v_fma_f32 v8, -v8, v11, v10
	v_div_fmas_f32 v8, v8, v9, v11
	v_div_fixup_f32 v4, v8, v7, v141
	ds_write_b32 v1, v4
	v_add_u32_e32 v1, 0x400, v1
	s_waitcnt vmcnt(3)
	v_mul_f32_e32 v7, 0xbfb8aa3b, v142
	v_exp_f32_e32 v7, v7
	s_nop 0
	v_add_f32_e32 v7, 1.0, v7
	v_div_scale_f32 v8, s[28:29], v7, v7, v142
	v_rcp_f32_e32 v9, v8
	v_div_scale_f32 v10, vcc, v142, v7, v142
	v_fma_f32 v11, -v8, v9, 1.0
	v_fmac_f32_e32 v9, v11, v9
	v_mul_f32_e32 v11, v10, v9
	v_fma_f32 v12, -v8, v11, v10
	v_fmac_f32_e32 v11, v12, v9
	v_fma_f32 v8, -v8, v11, v10
	v_div_fmas_f32 v8, v8, v9, v11
	v_div_fixup_f32 v4, v8, v7, v142
	ds_write_b32 v1, v4
	v_add_u32_e32 v1, 0x400, v1
	s_waitcnt vmcnt(2)
	v_mul_f32_e32 v7, 0xbfb8aa3b, v143
	v_exp_f32_e32 v7, v7
	s_nop 0
	v_add_f32_e32 v7, 1.0, v7
	v_div_scale_f32 v8, s[28:29], v7, v7, v143
	v_rcp_f32_e32 v9, v8
	v_div_scale_f32 v10, vcc, v143, v7, v143
	v_fma_f32 v11, -v8, v9, 1.0
	v_fmac_f32_e32 v9, v11, v9
	v_mul_f32_e32 v11, v10, v9
	v_fma_f32 v12, -v8, v11, v10
	v_fmac_f32_e32 v11, v12, v9
	v_fma_f32 v8, -v8, v11, v10
	v_div_fmas_f32 v8, v8, v9, v11
	v_div_fixup_f32 v4, v8, v7, v143
	ds_write_b32 v1, v4
	v_add_u32_e32 v1, 0x400, v1
	s_waitcnt vmcnt(1)
	v_mul_f32_e32 v7, 0xbfb8aa3b, v144
	v_exp_f32_e32 v7, v7
	s_nop 0
	v_add_f32_e32 v7, 1.0, v7
	v_div_scale_f32 v8, s[28:29], v7, v7, v144
	v_rcp_f32_e32 v9, v8
	v_div_scale_f32 v10, vcc, v144, v7, v144
	v_fma_f32 v11, -v8, v9, 1.0
	v_fmac_f32_e32 v9, v11, v9
	v_mul_f32_e32 v11, v10, v9
	v_fma_f32 v12, -v8, v11, v10
	v_fmac_f32_e32 v11, v12, v9
	v_fma_f32 v8, -v8, v11, v10
	v_div_fmas_f32 v8, v8, v9, v11
	v_div_fixup_f32 v4, v8, v7, v144
	ds_write_b32 v1, v4
	v_add_u32_e32 v1, 0x400, v1
	s_waitcnt vmcnt(0)
	v_mul_f32_e32 v7, 0xbfb8aa3b, v145
	v_exp_f32_e32 v7, v7
	s_nop 0
	v_add_f32_e32 v7, 1.0, v7
	v_div_scale_f32 v8, s[28:29], v7, v7, v145
	v_rcp_f32_e32 v9, v8
	v_div_scale_f32 v10, vcc, v145, v7, v145
	v_fma_f32 v11, -v8, v9, 1.0
	v_fmac_f32_e32 v9, v11, v9
	v_mul_f32_e32 v11, v10, v9
	v_fma_f32 v12, -v8, v11, v10
	v_fmac_f32_e32 v11, v12, v9
	v_fma_f32 v8, -v8, v11, v10
	v_div_fmas_f32 v8, v8, v9, v11
	v_div_fixup_f32 v4, v8, v7, v145
	ds_write_b32 v1, v4
	v_add_u32_e32 v1, 0x400, v1
